# scan loader: y-reduce LDS reads issued after the store part (before the poll and load issue) so their latency overlaps the load issue
# speedup vs baseline: 1.0108x; 1.0108x over previous
.Lscan_ld_steady_a:
	v_add_u32_e32 v38, s72, v91
	v_add_u32_e32 v95, v38, v92
	s_waitcnt vmcnt(19)
	v_lshlrev_b32_e32 v38, 16, v56
	v_and_b32_e32 v39, 0xffff0000, v56
	v_lshlrev_b32_e32 v40, 16, v57
	v_and_b32_e32 v41, 0xffff0000, v57
	ds_write_b128 v95, v[38:41] offset:4096
	s_waitcnt vmcnt(18)
	s_waitcnt vmcnt(17)
	s_waitcnt vmcnt(16)
	v_lshlrev_b32_e32 v38, 16, v58
	v_and_b32_e32 v39, 0xffff0000, v58
	v_lshlrev_b32_e32 v40, 16, v59
	v_and_b32_e32 v41, 0xffff0000, v59
	ds_write_b128 v95, v[38:41] offset:16384
	s_add_i32 s2, s49, -1
	s_lshl_b32 s3, s2, 14
	s_and_b32 s3, s3, 0x4000
	v_add_u32_e32 v4, s3, v126
	v_add_u32_e32 v8, s3, v127
	v_add_u32_e32 v16, s3, v128
	v_add_u32_e32 v20, s3, v129
	ds_read_b128 v[4:7], v4 offset:43008
	ds_read_b128 v[8:11], v8 offset:43008
	ds_read_b128 v[16:19], v16 offset:43008
	ds_read_b128 v[20:23], v20 offset:43008
	s_and_saveexec_b64 s[26:27], s[44:45]
	s_cbranch_execz .LBB0_1109
	v_lshlrev_b32_e32 v42, 2, v93
	v_lshlrev_b32_e32 v43, 2, v94
	v_add3_u32 v42, s72, v42, v43
	s_waitcnt vmcnt(15)
	v_lshlrev_b32_e32 v38, 16, v74
	v_and_b32_e32 v39, 0xffff0000, v74
	v_add_u32_e32 v42, 0x5000, v42
	v_lshlrev_b32_e32 v40, 16, v75
	v_and_b32_e32 v41, 0xffff0000, v75
	ds_write2_b32 v42, v38, v39 offset1:16
	ds_write2_b32 v42, v40, v41 offset0:32 offset1:48
	s_or_b64 exec, exec, s[26:27]
	s_cmpk_gt_u32 s49, 0x10b
	s_cbranch_scc0 .LBB0_1110

.LBB0_1165:
	s_or_b64 exec, exec, s[26:27]
	s_lshl_b32 s3, s49, 14
	s_and_b32 s3, s3, 0x4000
	v_add_u32_e32 v4, s3, v126
	v_add_u32_e32 v8, s3, v127
	v_add_u32_e32 v16, s3, v128
	v_add_u32_e32 v20, s3, v129
	ds_read_b128 v[4:7], v4 offset:43008
	ds_read_b128 v[8:11], v8 offset:43008
	ds_read_b128 v[16:19], v16 offset:43008
	ds_read_b128 v[20:23], v20 offset:43008
	s_cmpk_lt_u32 s49, 0x10b
	s_mov_b64 s[26:27], -1
	s_cbranch_scc0 .LBB0_1168

.LBB0_1167:
	s_lshl_b32 s3, s49, 14
	s_and_b32 s3, s3, 0x4000
	v_add_u32_e32 v4, s3, v126
	v_add_u32_e32 v8, s3, v127
	v_add_u32_e32 v16, s3, v128
	v_add_u32_e32 v20, s3, v129
	ds_read_b128 v[4:7], v4 offset:43008
	ds_read_b128 v[8:11], v8 offset:43008
	ds_read_b128 v[16:19], v16 offset:43008
	ds_read_b128 v[20:23], v20 offset:43008
	s_cmpk_lt_u32 s49, 0x10b
	s_mov_b64 s[26:27], -1
	s_cbranch_scc1 .LBB0_1166

.LBB0_1226:
	s_add_i32 s2, s49, 1
	s_lshl_b32 s3, s2, 14
	s_and_b32 s3, s3, 0x4000
	v_add_u32_e32 v4, s3, v126
	v_add_u32_e32 v8, s3, v127
	v_add_u32_e32 v16, s3, v128
	v_add_u32_e32 v20, s3, v129
	ds_read_b128 v[4:7], v4 offset:43008
	ds_read_b128 v[8:11], v8 offset:43008
	ds_read_b128 v[16:19], v16 offset:43008
	ds_read_b128 v[20:23], v20 offset:43008
	s_cmpk_gt_u32 s49, 0x109
	s_cbranch_scc1 .LBB0_1266
	s_cmp_gt_u32 s49, 9
	s_cselect_b64 s[26:27], -1, 0
	s_cmp_lt_u32 s49, 10
	s_cselect_b64 s[46:47], -1, 0
	s_cmp_gt_i32 s51, 6
	s_cselect_b64 s[60:61], -1, 0
	s_or_b64 s[46:47], s[46:47], s[60:61]
	s_and_b64 vcc, exec, s[46:47]
	s_cbranch_vccnz .LBB0_1242
	s_add_i32 s2, s49, -10
	s_sub_i32 s3, 0x109, s49
	s_cmpk_lt_u32 s49, 0x8a
	s_cselect_b32 s33, s2, s3
	s_cmp_lt_u32 s33, 24
	s_cbranch_scc1 .LBB0_1242
	s_lshl_b32 s2, s33, 3
	s_addk_i32 s2, 0xff47
	s_lshr_b32 s33, s2, 7
	s_cmp_gt_i32 s51, s33
	v_readlane_b32 s3, v250, 56
	s_cbranch_scc1 .LBB0_1241
